# GEMM K loop: fragment reads re-ordered (w0,t0..t3,w1..w3,t4..t7), first MFMA group waits per MFMA with counted lgkmcnt
# baseline (speedup 1.0000x reference)
.LBB0_246:
	s_add_i32 s10, s7, 0xffffa000
	s_cmp_lg_u32 s7, 0
	s_cselect_b32 s12, s10, 0xc000
	v_add_u32_e32 v131, s7, v150
	s_waitcnt vmcnt(6)
	s_barrier
	v_add_u32_e32 v133, s7, v149
	ds_read_b128 v[154:157], v131 offset:0
	ds_read_b128 v[170:173], v133 offset:0
	ds_read_b128 v[174:177], v133 offset:0x400
	ds_read_b128 v[178:181], v133 offset:0x800
	ds_read_b128 v[200:203], v133 offset:0xc00
	ds_read_b128 v[158:161], v131 offset:0x400
	ds_read_b128 v[162:165], v131 offset:0x800
	ds_read_b128 v[166:169], v131 offset:0xc00
	v_add_u32_e32 v131, s12, v147
	ds_read_b128 v[204:207], v133 offset:0x1000
	ds_read_b128 v[208:211], v133 offset:0x1400
	ds_read_b128 v[212:215], v133 offset:0x1800
	ds_read_b128 v[216:219], v133 offset:0x1c00
	s_add_u32 s10, s8, s50
	s_addc_u32 s11, s9, s51
	v_readfirstlane_b32 s13, v131
	s_add_u32 s64, s5, s100
	s_addc_u32 s65, s6, 0
	s_add_i32 s66, s7, 0x6000
	s_cmpk_lg_u32 s7, 0xc000
	s_cselect_b32 s7, s66, 0
	s_addk_i32 s100, 0x400
	s_add_u32 s50, s50, s60
	s_addc_u32 s51, s51, 0
	s_sub_i32 s68, s13, s12
	s_lshr_b32 s68, s68, 1
	s_add_i32 s68, s68, s12
	s_addk_i32 s68, 0x4000
	s_waitcnt lgkmcnt(10)
	v_mfma_f32_16x16x32_bf16 v[126:129], v[154:157], v[170:173], v[126:129]
	s_waitcnt lgkmcnt(9)
	v_mfma_f32_16x16x32_bf16 v[122:125], v[154:157], v[174:177], v[122:125]
	s_waitcnt lgkmcnt(8)
	v_mfma_f32_16x16x32_bf16 v[118:121], v[154:157], v[178:181], v[118:121]
	s_waitcnt lgkmcnt(7)
	v_mfma_f32_16x16x32_bf16 v[114:117], v[154:157], v[200:203], v[114:117]
	s_mov_b32 m0, s13
	s_waitcnt lgkmcnt(6)
	v_mfma_f32_16x16x32_bf16 v[110:113], v[158:161], v[170:173], v[110:113]
	global_load_lds_dwordx4 v0, s[10:11]
	v_mfma_f32_16x16x32_bf16 v[102:105], v[158:161], v[174:177], v[102:105]
	v_mfma_f32_16x16x32_bf16 v[94:97], v[158:161], v[178:181], v[94:97]
	s_add_u32 m0, s13, 0x400
	v_mfma_f32_16x16x32_bf16 v[86:89], v[158:161], v[200:203], v[86:89]
	global_load_lds_dwordx4 v130, s[10:11]
	s_waitcnt lgkmcnt(5)
	v_mfma_f32_16x16x32_bf16 v[78:81], v[162:165], v[170:173], v[78:81]
	v_mfma_f32_16x16x32_bf16 v[70:73], v[162:165], v[174:177], v[70:73]
	s_add_u32 m0, s13, 0x800
	v_mfma_f32_16x16x32_bf16 v[62:65], v[162:165], v[178:181], v[62:65]
	global_load_lds_dwordx4 v132, s[10:11]
	v_mfma_f32_16x16x32_bf16 v[54:57], v[162:165], v[200:203], v[54:57]
	s_waitcnt lgkmcnt(4)
	v_mfma_f32_16x16x32_bf16 v[46:49], v[166:169], v[170:173], v[46:49]
	s_add_u32 m0, s13, 0xc00
	v_mfma_f32_16x16x32_bf16 v[38:41], v[166:169], v[174:177], v[38:41]
	global_load_lds_dwordx4 v136, s[10:11]
	v_mfma_f32_16x16x32_bf16 v[30:33], v[166:169], v[178:181], v[30:33]
	v_mfma_f32_16x16x32_bf16 v[22:25], v[166:169], v[200:203], v[22:25]
	s_waitcnt lgkmcnt(0)
	v_mfma_f32_16x16x32_bf16 v[106:109], v[154:157], v[204:207], v[106:109]
	v_mfma_f32_16x16x32_bf16 v[98:101], v[154:157], v[208:211], v[98:101]
	s_mov_b32 m0, s68
	v_mfma_f32_16x16x32_bf16 v[90:93], v[154:157], v[212:215], v[90:93]
	global_load_lds_dwordx4 v138, s[64:65]
	v_mfma_f32_16x16x32_bf16 v[82:85], v[154:157], v[216:219], v[82:85]
	v_mfma_f32_16x16x32_bf16 v[74:77], v[158:161], v[204:207], v[74:77]
	v_mfma_f32_16x16x32_bf16 v[66:69], v[158:161], v[208:211], v[66:69]
	v_mfma_f32_16x16x32_bf16 v[58:61], v[158:161], v[212:215], v[58:61]
	v_mfma_f32_16x16x32_bf16 v[50:53], v[158:161], v[216:219], v[50:53]
	s_add_u32 m0, s68, 0x400
	v_mfma_f32_16x16x32_bf16 v[42:45], v[162:165], v[204:207], v[42:45]
	global_load_lds_dwordx4 v140, s[64:65]
	v_mfma_f32_16x16x32_bf16 v[34:37], v[162:165], v[208:211], v[34:37]
	v_mfma_f32_16x16x32_bf16 v[26:29], v[162:165], v[212:215], v[26:29]
	v_mfma_f32_16x16x32_bf16 v[18:21], v[162:165], v[216:219], v[18:21]
	v_mfma_f32_16x16x32_bf16 v[14:17], v[166:169], v[204:207], v[14:17]
	v_mfma_f32_16x16x32_bf16 v[10:13], v[166:169], v[208:211], v[10:13]
	v_mfma_f32_16x16x32_bf16 v[6:9], v[166:169], v[212:215], v[6:9]
	v_mfma_f32_16x16x32_bf16 v[2:5], v[166:169], v[216:219], v[2:5]
	s_cmpk_lg_i32 s100, 0x7800
	s_cbranch_scc1 .LBB0_246
	s_waitcnt vmcnt(6)
	s_barrier
	v_add_u32_e32 v0, s7, v150
	v_add_u32_e32 v140, s7, v149
	ds_read_b128 v[130:133], v0 offset:0
	ds_read_b128 v[136:139], v0 offset:0x400
	ds_read_b128 v[154:157], v0 offset:0x800
	ds_read_b128 v[158:161], v0 offset:0xc00
	ds_read_b128 v[162:165], v140 offset:0
	ds_read_b128 v[166:169], v140 offset:0x400
	ds_read_b128 v[170:173], v140 offset:0x800
	ds_read_b128 v[174:177], v140 offset:0xc00
	ds_read_b128 v[178:181], v140 offset:0x1000
	ds_read_b128 v[200:203], v140 offset:0x1400
	ds_read_b128 v[204:207], v140 offset:0x1800
	ds_read_b128 v[208:211], v140 offset:0x1c00
	s_lshl_b32 s49, s4, 8
	s_waitcnt lgkmcnt(4)
	s_nop 0
	v_mfma_f32_16x16x32_bf16 v[126:129], v[130:133], v[162:165], v[126:129]
	v_mfma_f32_16x16x32_bf16 v[118:121], v[130:133], v[170:173], v[118:121]
	v_mfma_f32_16x16x32_bf16 v[114:117], v[130:133], v[174:177], v[114:117]
	v_mfma_f32_16x16x32_bf16 v[110:113], v[136:139], v[162:165], v[110:113]
	v_mfma_f32_16x16x32_bf16 v[102:105], v[136:139], v[166:169], v[102:105]
	v_mfma_f32_16x16x32_bf16 v[94:97], v[136:139], v[170:173], v[94:97]
	v_mfma_f32_16x16x32_bf16 v[86:89], v[136:139], v[174:177], v[86:89]
	v_mfma_f32_16x16x32_bf16 v[70:73], v[154:157], v[166:169], v[70:73]
	v_mfma_f32_16x16x32_bf16 v[62:65], v[154:157], v[170:173], v[62:65]
	v_mfma_f32_16x16x32_bf16 v[54:57], v[154:157], v[174:177], v[54:57]
	v_mfma_f32_16x16x32_bf16 v[46:49], v[158:161], v[162:165], v[46:49]
	v_mfma_f32_16x16x32_bf16 v[38:41], v[158:161], v[166:169], v[38:41]
	v_mfma_f32_16x16x32_bf16 v[30:33], v[158:161], v[170:173], v[30:33]
	v_mfma_f32_16x16x32_bf16 v[22:25], v[158:161], v[174:177], v[22:25]
	v_mfma_f32_16x16x32_bf16 v[212:215], v[130:133], v[166:169], v[122:125]
	v_mfma_f32_16x16x32_bf16 v[216:219], v[154:157], v[162:165], v[78:81]
	s_waitcnt lgkmcnt(0)
	s_nop 0
	v_mfma_f32_16x16x32_bf16 v[174:177], v[136:139], v[178:181], v[74:77]
	v_mfma_f32_16x16x32_bf16 v[220:223], v[136:139], v[200:203], v[66:69]
	v_mfma_f32_16x16x32_bf16 v[224:227], v[136:139], v[204:207], v[58:61]
	v_mfma_f32_16x16x32_bf16 v[50:53], v[136:139], v[208:211], v[50:53]
	v_mfma_f32_16x16x32_bf16 v[136:139], v[154:157], v[178:181], v[42:45]
	v_mfma_f32_16x16x32_bf16 v[34:37], v[154:157], v[200:203], v[34:37]
	v_mfma_f32_16x16x32_bf16 v[6:9], v[158:161], v[204:207], v[6:9]
	v_mfma_f32_16x16x32_bf16 v[162:165], v[130:133], v[178:181], v[106:109]
	v_mfma_f32_16x16x32_bf16 v[166:169], v[130:133], v[200:203], v[98:101]
	v_mfma_f32_16x16x32_bf16 v[170:173], v[130:133], v[204:207], v[90:93]
	v_mfma_f32_16x16x32_bf16 v[130:133], v[130:133], v[208:211], v[82:85]
	v_mfma_f32_16x16x32_bf16 v[228:231], v[154:157], v[204:207], v[26:29]
	v_mfma_f32_16x16x32_bf16 v[154:157], v[154:157], v[208:211], v[18:21]
	v_mfma_f32_16x16x32_bf16 v[178:181], v[158:161], v[178:181], v[14:17]
	v_mfma_f32_16x16x32_bf16 v[200:203], v[158:161], v[200:203], v[10:13]
	v_mfma_f32_16x16x32_bf16 v[158:161], v[158:161], v[208:211], v[2:5]
	s_waitcnt vmcnt(0)
	s_barrier
	ds_read_b128 v[2:5], v151 offset:0
	ds_read_b128 v[14:17], v151 offset:0x400
	ds_read_b128 v[204:207], v151 offset:0x800
	ds_read_b128 v[208:211], v151 offset:0xc00
	ds_read_b128 v[10:13], v152 offset:0
	ds_read_b128 v[18:21], v152 offset:0x400
	ds_read_b128 v[26:29], v152 offset:0x800
	ds_read_b128 v[42:45], v152 offset:0xc00
	ds_read_b128 v[232:235], v152 offset:0x1000
	ds_read_b128 v[236:239], v152 offset:0x1400
	ds_read_b128 v[240:243], v152 offset:0x1800
	ds_read_b128 v[244:247], v152 offset:0x1c00
	s_nop 0
	s_waitcnt lgkmcnt(4)
	s_nop 0
	v_mfma_f32_16x16x32_bf16 v[122:125], v[2:5], v[10:13], v[126:129]
	v_mfma_f32_16x16x32_bf16 v[106:109], v[2:5], v[18:21], v[212:215]
	v_mfma_f32_16x16x32_bf16 v[90:93], v[2:5], v[26:29], v[118:121]
	v_mfma_f32_16x16x32_bf16 v[74:77], v[2:5], v[42:45], v[114:117]
	v_mfma_f32_16x16x32_bf16 v[126:129], v[14:17], v[10:13], v[110:113]
	v_mfma_f32_16x16x32_bf16 v[110:113], v[14:17], v[18:21], v[102:105]
	v_mfma_f32_16x16x32_bf16 v[94:97], v[14:17], v[26:29], v[94:97]
	v_mfma_f32_16x16x32_bf16 v[78:81], v[14:17], v[42:45], v[86:89]
	v_mfma_f32_16x16x32_bf16 v[114:117], v[204:207], v[10:13], v[216:219]
	v_mfma_f32_16x16x32_bf16 v[98:101], v[204:207], v[18:21], v[70:73]
	v_mfma_f32_16x16x32_bf16 v[82:85], v[204:207], v[26:29], v[62:65]
	v_mfma_f32_16x16x32_bf16 v[66:69], v[204:207], v[42:45], v[54:57]
	v_mfma_f32_16x16x32_bf16 v[118:121], v[208:211], v[10:13], v[46:49]
	v_mfma_f32_16x16x32_bf16 v[102:105], v[208:211], v[18:21], v[38:41]
	v_mfma_f32_16x16x32_bf16 v[86:89], v[208:211], v[26:29], v[30:33]
	v_mfma_f32_16x16x32_bf16 v[70:73], v[208:211], v[42:45], v[22:25]
	s_waitcnt lgkmcnt(0)
	s_nop 0
	v_mfma_f32_16x16x32_bf16 v[58:61], v[2:5], v[232:235], v[162:165]
	v_mfma_f32_16x16x32_bf16 v[42:45], v[2:5], v[236:239], v[166:169]
	v_mfma_f32_16x16x32_bf16 v[26:29], v[2:5], v[240:243], v[170:173]
	v_mfma_f32_16x16x32_bf16 v[10:13], v[2:5], v[244:247], v[130:133]
	v_mfma_f32_16x16x32_bf16 v[62:65], v[14:17], v[232:235], v[174:177]
	v_mfma_f32_16x16x32_bf16 v[46:49], v[14:17], v[236:239], v[220:223]
	v_mfma_f32_16x16x32_bf16 v[30:33], v[14:17], v[240:243], v[224:227]
	v_mfma_f32_16x16x32_bf16 v[14:17], v[14:17], v[244:247], v[50:53]
	v_mfma_f32_16x16x32_bf16 v[50:53], v[204:207], v[232:235], v[136:139]
	v_mfma_f32_16x16x32_bf16 v[34:37], v[204:207], v[236:239], v[34:37]
	v_mfma_f32_16x16x32_bf16 v[18:21], v[204:207], v[240:243], v[228:231]
	v_mfma_f32_16x16x32_bf16 v[2:5], v[204:207], v[244:247], v[154:157]
	v_mfma_f32_16x16x32_bf16 v[54:57], v[208:211], v[232:235], v[178:181]
	v_mfma_f32_16x16x32_bf16 v[38:41], v[208:211], v[236:239], v[200:203]
	v_mfma_f32_16x16x32_bf16 v[22:25], v[208:211], v[240:243], v[6:9]
	v_mfma_f32_16x16x32_bf16 v[6:9], v[208:211], v[244:247], v[158:161]
	v_mov_b32_e32 v136, v134
	s_mov_b64 s[50:51], -1
	s_and_b64 vcc, exec, s[22:23]
	s_barrier
	s_cbranch_vccz .LBB0_264
	s_and_b64 vcc, exec, s[0:1]
	s_cbranch_vccz .LBB0_250
	v_lshrrev_b32_e32 v0, 6, v136
	v_mul_lo_u32 v137, v0, s14
	v_and_b32_e32 v130, 15, v136
	v_and_or_b32 v0, v136, 48, v137
	s_movk_i32 s4, 0x90
	v_mad_u32_u24 v0, v130, s4, v0
	v_cvt_pk_bf16_f32 v130, v122, v123
	v_cvt_pk_bf16_f32 v131, v124, v125
	v_cvt_pk_bf16_f32 v132, v126, v127
	v_cvt_pk_bf16_f32 v133, v128, v129
	s_waitcnt vmcnt(0)
	ds_write_b128 v0, v[130:133]
	v_cvt_pk_bf16_f32 v130, v114, v115
	v_cvt_pk_bf16_f32 v131, v116, v117
	v_cvt_pk_bf16_f32 v132, v118, v119
	v_cvt_pk_bf16_f32 v133, v120, v121
	ds_write_b128 v0, v[130:133] offset:64
	v_cvt_pk_bf16_f32 v130, v106, v107
	v_cvt_pk_bf16_f32 v131, v108, v109
	v_cvt_pk_bf16_f32 v132, v110, v111
	v_cvt_pk_bf16_f32 v133, v112, v113
	ds_write_b128 v0, v[130:133] offset:2304
	v_cvt_pk_bf16_f32 v130, v98, v99
	v_cvt_pk_bf16_f32 v131, v100, v101
	v_cvt_pk_bf16_f32 v132, v102, v103
	v_cvt_pk_bf16_f32 v133, v104, v105
	ds_write_b128 v0, v[130:133] offset:2368
	v_cvt_pk_bf16_f32 v130, v90, v91
	v_cvt_pk_bf16_f32 v131, v92, v93
	v_cvt_pk_bf16_f32 v132, v94, v95
	v_cvt_pk_bf16_f32 v133, v96, v97
	ds_write_b128 v0, v[130:133] offset:4608
	v_cvt_pk_bf16_f32 v130, v82, v83
	v_cvt_pk_bf16_f32 v131, v84, v85
	v_cvt_pk_bf16_f32 v132, v86, v87
	v_cvt_pk_bf16_f32 v133, v88, v89
	ds_write_b128 v0, v[130:133] offset:4672
	v_cvt_pk_bf16_f32 v130, v74, v75
	v_cvt_pk_bf16_f32 v131, v76, v77
	v_cvt_pk_bf16_f32 v132, v78, v79
	v_cvt_pk_bf16_f32 v133, v80, v81
	ds_write_b128 v0, v[130:133] offset:6912
	v_cvt_pk_bf16_f32 v130, v66, v67
	v_cvt_pk_bf16_f32 v131, v68, v69
	v_cvt_pk_bf16_f32 v132, v70, v71
	v_cvt_pk_bf16_f32 v133, v72, v73
	ds_write_b128 v0, v[130:133] offset:6976
	v_cvt_pk_bf16_f32 v130, v58, v59
	v_cvt_pk_bf16_f32 v131, v60, v61
	v_cvt_pk_bf16_f32 v132, v62, v63
	v_cvt_pk_bf16_f32 v133, v64, v65
	ds_write_b128 v0, v[130:133] offset:9216
	v_cvt_pk_bf16_f32 v130, v50, v51
	v_cvt_pk_bf16_f32 v131, v52, v53
	v_cvt_pk_bf16_f32 v132, v54, v55
	v_cvt_pk_bf16_f32 v133, v56, v57
	ds_write_b128 v0, v[130:133] offset:9280
	v_cvt_pk_bf16_f32 v130, v42, v43
	v_cvt_pk_bf16_f32 v131, v44, v45
	v_cvt_pk_bf16_f32 v132, v46, v47
	v_cvt_pk_bf16_f32 v133, v48, v49
	ds_write_b128 v0, v[130:133] offset:11520
	v_cvt_pk_bf16_f32 v130, v34, v35
	v_cvt_pk_bf16_f32 v131, v36, v37
	v_cvt_pk_bf16_f32 v132, v38, v39
	v_cvt_pk_bf16_f32 v133, v40, v41
	ds_write_b128 v0, v[130:133] offset:11584
	v_cvt_pk_bf16_f32 v130, v26, v27
	v_cvt_pk_bf16_f32 v131, v28, v29
	v_cvt_pk_bf16_f32 v132, v30, v31
	v_cvt_pk_bf16_f32 v133, v32, v33
	ds_write_b128 v0, v[130:133] offset:13824
	v_cvt_pk_bf16_f32 v130, v18, v19
	v_cvt_pk_bf16_f32 v131, v20, v21
	v_cvt_pk_bf16_f32 v132, v22, v23
	v_cvt_pk_bf16_f32 v133, v24, v25
	ds_write_b128 v0, v[130:133] offset:13888
	v_cvt_pk_bf16_f32 v130, v10, v11
	v_cvt_pk_bf16_f32 v131, v12, v13
	v_cvt_pk_bf16_f32 v132, v14, v15
	v_cvt_pk_bf16_f32 v133, v16, v17
	ds_write_b128 v0, v[130:133] offset:16128
	v_cvt_pk_bf16_f32 v130, v2, v3
	v_cvt_pk_bf16_f32 v131, v4, v5
	v_cvt_pk_bf16_f32 v132, v6, v7
	v_cvt_pk_bf16_f32 v133, v8, v9
	ds_write_b128 v0, v[130:133] offset:16192
	v_and_b32_e32 v0, 0xffffff80, v136
	v_add_u32_e32 v130, s48, v0
	v_ashrrev_i32_e32 v131, 31, v130
	v_lshlrev_b64 v[130:131], 11, v[130:131]
	v_lshl_add_u64 v[130:131], s[38:39], 0, v[130:131]
	v_and_b32_e32 v0, 64, v136
	v_lshl_add_u64 v[130:131], s[46:47], 1, v[130:131]
	v_lshlrev_b32_e32 v0, 1, v0
	v_lshl_add_u64 v[138:139], v[130:131], 0, v[0:1]
	v_lshlrev_b32_e32 v0, 4, v136
	v_and_b32_e32 v0, 0x70, v0
	v_bfe_u32 v140, v136, 3, 3
	v_or_b32_e32 v130, v137, v0
	s_waitcnt lgkmcnt(0)
	v_mad_u32_u24 v137, v140, s4, v130
	ds_read_b128 v[66:69], v137
	ds_read_b128 v[70:73], v137 offset:1152
	ds_read_b128 v[74:77], v137 offset:2304
	ds_read_b128 v[78:81], v137 offset:3456
	ds_read_b128 v[82:85], v137 offset:4608
	ds_read_b128 v[86:89], v137 offset:5760
	ds_read_b128 v[90:93], v137 offset:6912
	ds_read_b128 v[94:97], v137 offset:8064
	ds_read_b128 v[98:101], v137 offset:9216
	ds_read_b128 v[102:105], v137 offset:10368
	ds_read_b128 v[106:109], v137 offset:11520
	ds_read_b128 v[110:113], v137 offset:12672
	ds_read_b128 v[114:117], v137 offset:13824
	ds_read_b128 v[118:121], v137 offset:14976
	ds_read_b128 v[122:125], v137 offset:16128
	ds_read_b128 v[126:129], v137 offset:17280
	v_lshl_add_u64 v[138:139], v[138:139], 0, v[0:1]
	v_lshlrev_b32_e32 v0, 11, v140
	v_lshl_add_u64 v[140:141], v[138:139], 0, v[0:1]
	s_mov_b64 s[50:51], 0
	s_waitcnt lgkmcnt(15)
	global_store_dwordx4 v[140:141], v[66:69], off
	v_or_b32_e32 v140, 0x4000, v0
	v_mov_b32_e32 v141, v1
	v_lshl_add_u64 v[140:141], v[138:139], 0, v[140:141]
	s_waitcnt lgkmcnt(14)
	global_store_dwordx4 v[140:141], v[70:73], off
	v_or_b32_e32 v140, 0x8000, v0
	v_mov_b32_e32 v141, v1
	v_lshl_add_u64 v[140:141], v[138:139], 0, v[140:141]
	s_waitcnt lgkmcnt(13)
	global_store_dwordx4 v[140:141], v[74:77], off
	v_or_b32_e32 v140, 0xc000, v0
	v_mov_b32_e32 v141, v1
	v_lshl_add_u64 v[140:141], v[138:139], 0, v[140:141]
	s_waitcnt lgkmcnt(12)
	global_store_dwordx4 v[140:141], v[78:81], off
	v_or_b32_e32 v140, 0x10000, v0
	v_mov_b32_e32 v141, v1
	v_lshl_add_u64 v[140:141], v[138:139], 0, v[140:141]
	s_waitcnt lgkmcnt(11)
	global_store_dwordx4 v[140:141], v[82:85], off
	v_or_b32_e32 v140, 0x14000, v0
	v_mov_b32_e32 v141, v1
	v_lshl_add_u64 v[140:141], v[138:139], 0, v[140:141]
	s_waitcnt lgkmcnt(10)
	global_store_dwordx4 v[140:141], v[86:89], off
	v_or_b32_e32 v140, 0x18000, v0
	v_mov_b32_e32 v141, v1
	v_lshl_add_u64 v[140:141], v[138:139], 0, v[140:141]
	s_waitcnt lgkmcnt(9)
	global_store_dwordx4 v[140:141], v[90:93], off
	v_or_b32_e32 v140, 0x1c000, v0
	v_mov_b32_e32 v141, v1
	v_lshl_add_u64 v[140:141], v[138:139], 0, v[140:141]
	s_waitcnt lgkmcnt(8)
	global_store_dwordx4 v[140:141], v[94:97], off
	v_or_b32_e32 v140, 0x20000, v0
	v_mov_b32_e32 v141, v1
	v_lshl_add_u64 v[140:141], v[138:139], 0, v[140:141]
	s_waitcnt lgkmcnt(7)
	global_store_dwordx4 v[140:141], v[98:101], off
	v_or_b32_e32 v140, 0x24000, v0
	v_mov_b32_e32 v141, v1
	v_lshl_add_u64 v[140:141], v[138:139], 0, v[140:141]
	s_waitcnt lgkmcnt(6)
	global_store_dwordx4 v[140:141], v[102:105], off
	v_or_b32_e32 v140, 0x28000, v0
	v_mov_b32_e32 v141, v1
	v_lshl_add_u64 v[140:141], v[138:139], 0, v[140:141]
	s_waitcnt lgkmcnt(5)
	global_store_dwordx4 v[140:141], v[106:109], off
	v_or_b32_e32 v140, 0x2c000, v0
	v_mov_b32_e32 v141, v1
	v_lshl_add_u64 v[140:141], v[138:139], 0, v[140:141]
	s_waitcnt lgkmcnt(4)
	global_store_dwordx4 v[140:141], v[110:113], off
	v_or_b32_e32 v140, 0x30000, v0
	v_mov_b32_e32 v141, v1
	v_lshl_add_u64 v[140:141], v[138:139], 0, v[140:141]
	s_waitcnt lgkmcnt(3)
	global_store_dwordx4 v[140:141], v[114:117], off
	v_or_b32_e32 v140, 0x34000, v0
	v_mov_b32_e32 v141, v1
	v_lshl_add_u64 v[140:141], v[138:139], 0, v[140:141]
	s_waitcnt lgkmcnt(2)
	global_store_dwordx4 v[140:141], v[118:121], off
	v_or_b32_e32 v140, 0x38000, v0
	v_mov_b32_e32 v141, v1
	v_lshl_add_u64 v[140:141], v[138:139], 0, v[140:141]
	v_or_b32_e32 v0, 0x3c000, v0
	s_waitcnt lgkmcnt(1)
	global_store_dwordx4 v[140:141], v[122:125], off
	v_lshl_add_u64 v[138:139], v[138:139], 0, v[0:1]
	s_waitcnt lgkmcnt(0)
	global_store_dwordx4 v[138:139], v[126:129], off
	s_waitcnt lgkmcnt(0)
	s_barrier
